# plus MLA prompt store_o gate loads prefetched at item start (8 x dwordx2 into spare VGPRs)
# baseline (speedup 1.0000x reference)
; DI void store_o(const P& p, const f32x16 (&o)[2], float inv, size_t tok, int colbase, int lh) {
;     ...
;       const size_t off = tok * 1024 + colbase + dvt * 32 + g * 8 + lh * 4;
;       const u32x2 gt = *(const u32x2*)(gates + off);
; DI void mla_item(const P& p, char* smem, int b, int hd, int q0, bool samp) {
;     ...
;     const u16* qp = (const u16*)(p.ws + OFF_QMLA) + (tokrow0 + qw0 + l32) * 768 + hw * 96 + lh * 8;
; #pragma unroll
;     for (int ks = 0; ks < 6; ++ks) qf[ks] = *(const bf16x8*)(qp + ks * 16);
.LBB0_393:
	s_and_b64 vcc, exec, s[4:5]
	s_cbranch_vccz .LBB0_426
	s_add_i32 s4, s85, 0xffffff40
	s_and_b32 s5, s4, 0xffffff00
	v_mov_b32_e32 v1, v152
	s_sub_i32 s60, 0x700, s5
	s_lshl_b32 s62, s4, 8
	v_readfirstlane_b32 s5, v1
	s_ashr_i32 s5, s5, 1
	s_and_b32 s61, s5, 0xffffffe0
	s_add_i32 s61, s61, s60
	v_and_b32_e32 v14, 31, v1
	s_ashr_i32 s63, s61, 31
	s_and_b32 s46, s62, 0xf800
	v_or_b32_e32 v4, s61, v14
	v_mov_b32_e32 v5, s63
	v_lshl_add_u64 v[104:105], v[4:5], 0, s[46:47]
	v_mov_b64_e32 v[4:5], s[36:37]
	v_mad_u64_u32 v[4:5], s[4:5], v104, s76, v[4:5]
	v_bfe_u32 v146, v1, 5, 1
	v_mad_i32_i24 v5, v105, s76, v5
	s_mul_i32 s4, s86, 0xc0
	s_mov_b32 s5, s47
	v_lshl_add_u64 v[4:5], v[4:5], 0, s[4:5]
	v_lshlrev_b32_e32 v106, 4, v146
	v_mov_b32_e32 v107, v3
	v_ashrrev_i32_e32 v44, 3, v1
	v_lshl_add_u64 v[4:5], v[4:5], 0, v[106:107]
	v_ashrrev_i32_e32 v45, 31, v44
	global_load_dwordx4 v[88:91], v[4:5], off
	global_load_dwordx4 v[84:87], v[4:5], off offset:32
	global_load_dwordx4 v[80:83], v[4:5], off offset:64
	global_load_dwordx4 v[76:79], v[4:5], off offset:96
	global_load_dwordx4 v[72:75], v[4:5], off offset:128
	global_load_dwordx4 v[68:71], v[4:5], off offset:160
	s_lshl_b32 s98, s86, 6
	v_lshlrev_b64 v[248:249], 10, v[104:105]
	v_lshlrev_b32_e32 v250, 2, v146
	v_or3_b32 v248, v248, s98, v250
	v_or_b32_e32 v248, 0x200, v248
	v_lshlrev_b64 v[248:249], 1, v[248:249]
	v_lshl_add_u64 v[248:249], s[22:23], 0, v[248:249]
	global_load_dwordx2 v[232:233], v[248:249], off
	global_load_dwordx2 v[234:235], v[248:249], off offset:16
	global_load_dwordx2 v[236:237], v[248:249], off offset:32
	global_load_dwordx2 v[238:239], v[248:249], off offset:48
	global_load_dwordx2 v[240:241], v[248:249], off offset:64
	global_load_dwordx2 v[242:243], v[248:249], off offset:80
	global_load_dwordx2 v[244:245], v[248:249], off offset:96
	global_load_dwordx2 v[246:247], v[248:249], off offset:112
	v_lshl_add_u64 v[4:5], v[44:45], 0, s[46:47]
	v_lshlrev_b64 v[4:5], 11, v[4:5]
	v_lshlrev_b32_e32 v12, 3, v1
	v_lshl_add_u64 v[4:5], s[26:27], 0, v[4:5]
	s_lshl_b32 s52, s86, 8
	s_mov_b32 s53, s47
	v_and_b32_e32 v2, 56, v12
	v_lshl_add_u64 v[4:5], v[4:5], 0, s[52:53]
	v_lshlrev_b32_e32 v2, 1, v2
	v_lshl_add_u64 v[4:5], v[4:5], 0, v[2:3]
	global_load_dwordx4 v[8:11], v[4:5], off
	s_nop 0
	global_load_dwordx4 v[4:7], v[4:5], off offset:128
	v_and_b32_e32 v12, 24, v12
	v_cmp_lt_i32_e32 vcc, s73, v1
	v_cmp_gt_i32_e64 s[4:5], s77, v1
	s_waitcnt vmcnt(10)
	v_mov_b32_e32 v92, v3
	v_mov_b32_e32 v93, v3
	v_mov_b32_e32 v94, v3
	v_mov_b32_e32 v95, v3
	v_ashrrev_i32_e32 v15, 2, v1
	v_lshlrev_b32_e32 v12, 1, v12
	s_and_saveexec_b64 s[6:7], s[4:5]
	s_cbranch_execz .LBB0_396
	v_ashrrev_i32_e32 v16, 2, v1
	v_ashrrev_i32_e32 v17, 31, v16
	v_lshl_add_u64 v[16:17], v[16:17], 0, s[46:47]
	v_lshlrev_b64 v[16:17], 6, v[16:17]
	v_lshl_add_u64 v[16:17], s[34:35], 0, v[16:17]
	v_mov_b32_e32 v13, v3
	v_lshl_add_u64 v[16:17], v[16:17], 0, v[12:13]
	global_load_dwordx4 v[92:95], v[16:17], off

; DI float bflo(unsigned v) { return __uint_as_float(v << 16); }
; DI float bfhi(unsigned v) { return __uint_as_float(v & 0xffff0000u); }
; DI void store_o(const P& p, const f32x16 (&o)[2], float inv, size_t tok, int colbase, int lh) {
;   const u16* gates = (const u16*)(p.ws + OFF_GATES);
;   u16* mixed = (u16*)(p.ws + OFF_H);
; #pragma unroll
;   for (int dvt = 0; dvt < 2; ++dvt)
; #pragma unroll
;     for (int g = 0; g < 4; ++g) {
;       const size_t off = tok * 1024 + colbase + dvt * 32 + g * 8 + lh * 4;
;       const u32x2 gt = *(const u32x2*)(gates + off);
;       u32x2 ov = {pk2(o[dvt][4 * g + 0] * inv * bflo(gt.x), o[dvt][4 * g + 1] * inv * bfhi(gt.x)),
;                   pk2(o[dvt][4 * g + 2] * inv * bflo(gt.y), o[dvt][4 * g + 3] * inv * bfhi(gt.y))};
;       *(u32x2*)(mixed + off) = ov;
;     }
; }
; DI void mla_item(const P& p, char* smem, int b, int hd, int q0, bool samp) {
;     ...
;   if (active) {
;     const float lt = lsum + __shfl_xor(lsum, 32);
;     store_o(p, o, 1.f / lt, tokrow0 + qw0 + l32, 512 + hw * 64, lh);
;   }
.LBB0_425:
	s_lshl_b32 s4, s86, 6
	v_lshlrev_b64 v[52:53], 10, v[104:105]
	v_lshlrev_b32_e32 v1, 2, v146
	v_or3_b32 v1, v52, s4, v1
	v_or_b32_e32 v52, 0x200, v1
	v_lshlrev_b64 v[36:37], 1, v[52:53]
	v_lshl_add_u64 v[38:39], s[22:23], 0, v[36:37]
	v_or_b32_e32 v40, 16, v36
	v_mov_b32_e32 v41, v37
	s_barrier
	v_mov_b32_e32 v38, v232
	v_mov_b32_e32 v39, v233
	v_lshl_add_u64 v[42:43], s[22:23], 0, v[40:41]
	v_mov_b32_e32 v42, v234
	v_mov_b32_e32 v43, v235
	v_or_b32_e32 v44, 32, v36
	v_mov_b32_e32 v45, v37
	v_lshl_add_u64 v[46:47], s[22:23], 0, v[44:45]
	v_mov_b32_e32 v46, v236
	v_mov_b32_e32 v47, v237
	v_or_b32_e32 v48, 48, v36
	v_mov_b32_e32 v49, v37
	v_lshl_add_u64 v[50:51], s[22:23], 0, v[48:49]
	v_mov_b32_e32 v50, v238
	v_mov_b32_e32 v51, v239
	v_or_b32_e32 v56, 64, v36
	v_mov_b32_e32 v57, v37
	v_lshl_add_u64 v[54:55], s[22:23], 0, v[56:57]
	v_mov_b32_e32 v58, v240
	v_mov_b32_e32 v59, v241
	v_or_b32_e32 v62, 0x50, v36
	v_mov_b32_e32 v63, v37
	v_lshl_add_u64 v[54:55], s[22:23], 0, v[62:63]
	v_mov_b32_e32 v64, v242
	v_mov_b32_e32 v65, v243
	v_and_b32_e32 v52, 64, v154
	v_xor_b32_e32 v2, 32, v154
	v_add_u32_e32 v52, 64, v52
	v_cmp_lt_i32_e32 vcc, v2, v52
	v_or_b32_e32 v52, 0x238, v1
	v_lshl_add_u64 v[60:61], s[24:25], 0, v[36:37]
	v_or_b32_e32 v36, 0x60, v36
	v_lshl_add_u64 v[54:55], v[52:53], 1, s[22:23]
	v_lshl_add_u64 v[66:67], s[22:23], 0, v[36:37]
	v_mov_b32_e32 v66, v244
	v_mov_b32_e32 v67, v245
	s_nop 0
	v_mov_b32_e32 v54, v246
	v_mov_b32_e32 v55, v247
	v_cndmask_b32_e32 v2, v154, v2, vcc
	v_lshlrev_b32_e32 v2, 2, v2
	ds_bpermute_b32 v1, v2, v149
	v_lshl_add_u64 v[40:41], s[24:25], 0, v[40:41]
	s_mov_b64 s[52:53], -1
	s_waitcnt lgkmcnt(0)
	v_add_f32_e32 v1, v149, v1
	v_div_scale_f32 v2, s[4:5], v1, v1, 1.0
	v_rcp_f32_e32 v68, v2
	v_div_scale_f32 v69, vcc, 1.0, v1, 1.0
	v_fma_f32 v70, -v2, v68, 1.0
	v_fmac_f32_e32 v68, v70, v68
	v_mul_f32_e32 v70, v69, v68
	v_fma_f32 v71, -v2, v70, v69
	v_fmac_f32_e32 v70, v71, v68
	v_fma_f32 v2, -v2, v70, v69
	v_div_fmas_f32 v2, v2, v68, v70
	v_div_fixup_f32 v2, v2, v1, 1.0
	v_pk_mul_f32 v[20:21], v[20:21], v[2:3] op_sel_hi:[1,0]
	v_pk_mul_f32 v[22:23], v[22:23], v[2:3] op_sel_hi:[1,0]
	v_pk_mul_f32 v[24:25], v[24:25], v[2:3] op_sel_hi:[1,0]
	v_pk_mul_f32 v[26:27], v[26:27], v[2:3] op_sel_hi:[1,0]
	v_pk_mul_f32 v[28:29], v[28:29], v[2:3] op_sel_hi:[1,0]
	v_pk_mul_f32 v[30:31], v[30:31], v[2:3] op_sel_hi:[1,0]
	v_pk_mul_f32 v[4:5], v[4:5], v[2:3] op_sel_hi:[1,0]
	v_pk_mul_f32 v[6:7], v[6:7], v[2:3] op_sel_hi:[1,0]
	s_waitcnt vmcnt(7)
	v_lshlrev_b32_e32 v68, 16, v38
	v_and_b32_e32 v69, 0xffff0000, v38
	v_lshlrev_b32_e32 v38, 16, v39
	v_and_b32_e32 v39, 0xffff0000, v39
	v_pk_mul_f32 v[20:21], v[20:21], v[68:69]
	v_pk_mul_f32 v[22:23], v[22:23], v[38:39]
	s_waitcnt vmcnt(6)
	v_lshlrev_b32_e32 v38, 16, v42
	v_and_b32_e32 v39, 0xffff0000, v42
	v_lshlrev_b32_e32 v42, 16, v43
	v_and_b32_e32 v43, 0xffff0000, v43
	v_cvt_pk_bf16_f32 v20, v20, v21
	v_cvt_pk_bf16_f32 v21, v22, v23
	v_pk_mul_f32 v[22:23], v[24:25], v[38:39]
	v_pk_mul_f32 v[24:25], v[26:27], v[42:43]
	s_waitcnt vmcnt(5)
	v_lshlrev_b32_e32 v68, 16, v46
	v_and_b32_e32 v69, 0xffff0000, v46
	v_lshlrev_b32_e32 v46, 16, v47
	global_store_dwordx2 v[60:61], v[20:21], off
	v_cvt_pk_bf16_f32 v20, v22, v23
	v_cvt_pk_bf16_f32 v21, v24, v25
	v_and_b32_e32 v47, 0xffff0000, v47
	v_pk_mul_f32 v[26:27], v[28:29], v[68:69]
	global_store_dwordx2 v[40:41], v[20:21], off
	v_pk_mul_f32 v[20:21], v[30:31], v[46:47]
	v_cvt_pk_bf16_f32 v22, v26, v27
	v_cvt_pk_bf16_f32 v23, v20, v21
	v_lshl_add_u64 v[20:21], s[24:25], 0, v[44:45]
	global_store_dwordx2 v[20:21], v[22:23], off
	v_pk_mul_f32 v[20:21], v[32:33], v[2:3] op_sel_hi:[1,0]
	s_waitcnt vmcnt(7)
	v_lshlrev_b32_e32 v22, 16, v50
	v_and_b32_e32 v23, 0xffff0000, v50
	v_pk_mul_f32 v[20:21], v[20:21], v[22:23]
	v_pk_mul_f32 v[22:23], v[34:35], v[2:3] op_sel_hi:[1,0]
	v_lshlrev_b32_e32 v24, 16, v51
	v_and_b32_e32 v25, 0xffff0000, v51
	v_pk_mul_f32 v[22:23], v[22:23], v[24:25]
	v_cvt_pk_bf16_f32 v20, v20, v21
	v_cvt_pk_bf16_f32 v21, v22, v23
	v_lshl_add_u64 v[22:23], s[24:25], 0, v[48:49]
	global_store_dwordx2 v[22:23], v[20:21], off
	s_waitcnt vmcnt(7)
	v_lshlrev_b32_e32 v20, 16, v58
	v_and_b32_e32 v21, 0xffff0000, v58
	v_pk_mul_f32 v[4:5], v[4:5], v[20:21]
	v_lshlrev_b32_e32 v20, 16, v59
	v_and_b32_e32 v21, 0xffff0000, v59
	v_pk_mul_f32 v[6:7], v[6:7], v[20:21]
	v_cvt_pk_bf16_f32 v4, v4, v5
	v_cvt_pk_bf16_f32 v5, v6, v7
	v_lshl_add_u64 v[6:7], s[24:25], 0, v[56:57]
	global_store_dwordx2 v[6:7], v[4:5], off
	v_pk_mul_f32 v[4:5], v[8:9], v[2:3] op_sel_hi:[1,0]
	s_waitcnt vmcnt(7)
	v_lshlrev_b32_e32 v6, 16, v64
	v_and_b32_e32 v7, 0xffff0000, v64
	v_pk_mul_f32 v[4:5], v[4:5], v[6:7]
	v_pk_mul_f32 v[6:7], v[10:11], v[2:3] op_sel_hi:[1,0]
	v_lshlrev_b32_e32 v8, 16, v65
	v_and_b32_e32 v9, 0xffff0000, v65
	v_pk_mul_f32 v[6:7], v[6:7], v[8:9]
	v_cvt_pk_bf16_f32 v4, v4, v5
	v_cvt_pk_bf16_f32 v5, v6, v7
	v_lshl_add_u64 v[6:7], s[24:25], 0, v[62:63]
	global_store_dwordx2 v[6:7], v[4:5], off
	v_pk_mul_f32 v[4:5], v[12:13], v[2:3] op_sel_hi:[1,0]
	s_waitcnt vmcnt(7)
	v_lshlrev_b32_e32 v6, 16, v66
	v_and_b32_e32 v7, 0xffff0000, v66
	v_pk_mul_f32 v[4:5], v[4:5], v[6:7]
	v_pk_mul_f32 v[6:7], v[14:15], v[2:3] op_sel_hi:[1,0]
	v_lshlrev_b32_e32 v8, 16, v67
	v_and_b32_e32 v9, 0xffff0000, v67
	v_pk_mul_f32 v[6:7], v[6:7], v[8:9]
	v_cvt_pk_bf16_f32 v4, v4, v5
	v_cvt_pk_bf16_f32 v5, v6, v7
	v_lshl_add_u64 v[6:7], s[24:25], 0, v[36:37]
	global_store_dwordx2 v[6:7], v[4:5], off
	v_pk_mul_f32 v[4:5], v[16:17], v[2:3] op_sel_hi:[1,0]
	s_waitcnt vmcnt(7)
	v_lshlrev_b32_e32 v6, 16, v54
	v_and_b32_e32 v7, 0xffff0000, v54
	v_pk_mul_f32 v[4:5], v[4:5], v[6:7]
	s_nop 0
	v_cvt_pk_bf16_f32 v56, v4, v5
	v_mul_f32_e32 v4, v18, v2
	v_lshlrev_b32_e32 v18, 16, v55
	v_mov_b32_e32 v5, v2
	v_pk_mul_f32 v[18:19], v[4:5], v[18:19]
